# v48 + NA final attention step: 16 exec-masked bias LDS reads batched (unconditional reads + selects), as in the loop steps
# speedup vs baseline: 1.0066x; 1.0066x over previous
.LBB0_821:
	s_andn2_b64 vcc, exec, s[0:1]
	s_cbranch_vccnz .LBB0_857
	s_or_b32 s0, s2, 1
	s_add_i32 s0, s0, s89
	s_sub_i32 s1, s0, s20
	s_cmp_gt_u32 s1, 7
	s_cbranch_scc1 .LBB0_856
	v_readlane_b32 s1, v252, 37
	s_sub_i32 s0, s0, s1
	s_mulk_i32 s0, 0x7c
	s_add_i32 s0, s0, 0
	v_lshlrev_b32_e32 v14, 2, v233
	v_sub_u32_e32 v15, s0, v14
	v_lshlrev_b32_e32 v17, 4, v230
	s_mov_b32 s0, 0x15000
	v_add3_u32 v17, v15, v17, s0
	ds_read_b32 v64, v17 offset:928
	ds_read_b32 v65, v17 offset:932
	ds_read_b32 v66, v17 offset:936
	ds_read_b32 v67, v17 offset:940
	ds_read_b32 v68, v17 offset:960
	ds_read_b32 v69, v17 offset:964
	ds_read_b32 v70, v17 offset:968
	ds_read_b32 v71, v17 offset:972
	ds_read_b32 v72, v17 offset:992
	ds_read_b32 v73, v17 offset:996
	ds_read_b32 v74, v17 offset:1000
	ds_read_b32 v75, v17 offset:1004
	ds_read_b32 v76, v17 offset:1024
	ds_read_b32 v77, v17 offset:1028
	ds_read_b32 v78, v17 offset:1032
	ds_read_b32 v79, v17 offset:1036
	s_waitcnt lgkmcnt(0)
	ds_read_b32 v15, v17 offset:1056
	v_lshlrev_b32_e32 v14, 2, v230
	v_sub_u32_e32 v18, v14, v232
	v_cmp_gt_u32_e32 vcc, 16, v18
	v_sub_f32_e32 v64, v64, v231
	v_add_f32_e32 v64, v112, v64
	v_cndmask_b32_e32 v64, v16, v64, vcc
	v_or_b32_e32 v18, 1, v14
	v_sub_u32_e32 v18, v18, v232
	v_cmp_gt_u32_e32 vcc, 16, v18
	ds_read_b32 v18, v17 offset:1060
	v_sub_f32_e32 v65, v65, v231
	v_add_f32_e32 v65, v113, v65
	v_cndmask_b32_e32 v65, v16, v65, vcc
	ds_read_b32 v19, v17 offset:1064
	v_or_b32_e32 v20, 2, v14
	v_sub_u32_e32 v20, v20, v232
	v_cmp_gt_u32_e32 vcc, 16, v20
	v_sub_f32_e32 v66, v66, v231
	v_add_f32_e32 v66, v114, v66
	v_cndmask_b32_e32 v66, v16, v66, vcc
	v_or_b32_e32 v20, 3, v14
	v_sub_u32_e32 v20, v20, v232
	v_cmp_gt_u32_e32 vcc, 16, v20
	ds_read_b32 v20, v17 offset:1068
	v_sub_f32_e32 v67, v67, v231
	v_add_f32_e32 v67, v115, v67
	v_cndmask_b32_e32 v67, v16, v67, vcc
	ds_read_b32 v21, v17 offset:1088
	v_or_b32_e32 v22, 8, v14
	v_sub_u32_e32 v22, v22, v232
	v_cmp_gt_u32_e32 vcc, 16, v22
	v_sub_f32_e32 v68, v68, v231
	v_add_f32_e32 v68, v116, v68
	v_cndmask_b32_e32 v68, v16, v68, vcc
	v_or_b32_e32 v22, 9, v14
	v_sub_u32_e32 v22, v22, v232
	v_cmp_gt_u32_e32 vcc, 16, v22
	ds_read_b32 v22, v17 offset:1092
	v_sub_f32_e32 v69, v69, v231
	v_add_f32_e32 v69, v117, v69
	v_cndmask_b32_e32 v69, v16, v69, vcc
	ds_read_b32 v23, v17 offset:1096
	v_or_b32_e32 v24, 10, v14
	v_sub_u32_e32 v24, v24, v232
	v_cmp_gt_u32_e32 vcc, 16, v24
	v_sub_f32_e32 v70, v70, v231
	v_add_f32_e32 v70, v118, v70
	v_cndmask_b32_e32 v70, v16, v70, vcc
	v_or_b32_e32 v24, 11, v14
	v_sub_u32_e32 v24, v24, v232
	v_cmp_gt_u32_e32 vcc, 16, v24
	ds_read_b32 v24, v17 offset:1100
	v_sub_f32_e32 v71, v71, v231
	v_add_f32_e32 v71, v119, v71
	v_cndmask_b32_e32 v71, v16, v71, vcc
	ds_read_b32 v25, v17 offset:1120
	v_or_b32_e32 v26, 16, v14
	v_sub_u32_e32 v26, v26, v232
	v_cmp_gt_u32_e32 vcc, 16, v26
	v_sub_f32_e32 v72, v72, v231
	v_add_f32_e32 v72, v120, v72
	v_cndmask_b32_e32 v72, v16, v72, vcc
	v_or_b32_e32 v26, 17, v14
	v_sub_u32_e32 v26, v26, v232
	v_cmp_gt_u32_e32 vcc, 16, v26
	ds_read_b32 v26, v17 offset:1124
	v_sub_f32_e32 v73, v73, v231
	v_add_f32_e32 v73, v121, v73
	v_cndmask_b32_e32 v73, v16, v73, vcc
	ds_read_b32 v27, v17 offset:1128
	v_or_b32_e32 v28, 18, v14
	v_sub_u32_e32 v28, v28, v232
	v_cmp_gt_u32_e32 vcc, 16, v28
	v_sub_f32_e32 v74, v74, v231
	v_add_f32_e32 v74, v122, v74
	v_cndmask_b32_e32 v74, v16, v74, vcc
	v_or_b32_e32 v28, 19, v14
	v_sub_u32_e32 v28, v28, v232
	v_cmp_gt_u32_e32 vcc, 16, v28
	ds_read_b32 v28, v17 offset:1132
	v_sub_f32_e32 v75, v75, v231
	v_add_f32_e32 v75, v123, v75
	v_cndmask_b32_e32 v75, v16, v75, vcc
	ds_read_b32 v29, v17 offset:1152
	v_or_b32_e32 v30, 24, v14
	v_sub_u32_e32 v30, v30, v232
	v_cmp_gt_u32_e32 vcc, 16, v30
	v_sub_f32_e32 v76, v76, v231
	v_add_f32_e32 v76, v124, v76
	v_cndmask_b32_e32 v76, v16, v76, vcc
	v_or_b32_e32 v30, 25, v14
	v_sub_u32_e32 v30, v30, v232
	v_cmp_gt_u32_e32 vcc, 16, v30
	ds_read_b32 v30, v17 offset:1156
	v_sub_f32_e32 v77, v77, v231
	v_add_f32_e32 v77, v125, v77
	v_cndmask_b32_e32 v77, v16, v77, vcc
	ds_read_b32 v31, v17 offset:1160
	v_or_b32_e32 v241, 26, v14
	v_sub_u32_e32 v241, v241, v232
	v_cmp_gt_u32_e32 vcc, 16, v241
	v_sub_f32_e32 v78, v78, v231
	v_add_f32_e32 v78, v126, v78
	v_cndmask_b32_e32 v78, v16, v78, vcc
	ds_read_b32 v95, v17 offset:1164
	v_or_b32_e32 v80, 27, v14
	v_sub_u32_e32 v80, v80, v232
	v_cmp_gt_u32_e32 vcc, 16, v80
	v_sub_f32_e32 v79, v79, v231
	v_add_f32_e32 v79, v127, v79
	v_cndmask_b32_e32 v79, v16, v79, vcc
	v_or_b32_e32 v17, 32, v14
	v_sub_u32_e32 v17, v17, v232
	s_waitcnt lgkmcnt(14)
	v_sub_f32_e32 v15, v15, v231
	v_add_f32_e32 v15, v96, v15
	v_cmp_gt_u32_e32 vcc, 16, v17
	v_sub_f32_e32 v17, v18, v231
	v_add_f32_e32 v17, v97, v17
	v_cndmask_b32_e32 v80, v16, v15, vcc
	v_or_b32_e32 v15, 33, v14
	v_sub_u32_e32 v15, v15, v232
	v_cmp_gt_u32_e32 vcc, 16, v15
	v_or_b32_e32 v15, 34, v14
	v_sub_u32_e32 v15, v15, v232
	v_cndmask_b32_e32 v81, v16, v17, vcc
	s_waitcnt lgkmcnt(13)
	v_sub_f32_e32 v17, v19, v231
	v_add_f32_e32 v17, v98, v17
	v_cmp_gt_u32_e32 vcc, 16, v15
	v_or_b32_e32 v15, 35, v14
	v_sub_u32_e32 v15, v15, v232
	v_cndmask_b32_e32 v82, v16, v17, vcc
	s_waitcnt lgkmcnt(12)
	v_sub_f32_e32 v17, v20, v231
	v_add_f32_e32 v17, v99, v17
	v_cmp_gt_u32_e32 vcc, 16, v15
	v_or_b32_e32 v15, 40, v14
	v_sub_u32_e32 v15, v15, v232
	v_cndmask_b32_e32 v83, v16, v17, vcc
	s_waitcnt lgkmcnt(11)
	v_sub_f32_e32 v17, v21, v231
	v_add_f32_e32 v17, v100, v17
	v_cmp_gt_u32_e32 vcc, 16, v15
	v_or_b32_e32 v15, 41, v14
	v_sub_u32_e32 v15, v15, v232
	v_cndmask_b32_e32 v84, v16, v17, vcc
	s_waitcnt lgkmcnt(10)
	v_sub_f32_e32 v17, v22, v231
	v_add_f32_e32 v17, v101, v17
	v_cmp_gt_u32_e32 vcc, 16, v15
	v_or_b32_e32 v15, 42, v14
	v_sub_u32_e32 v15, v15, v232
	v_cndmask_b32_e32 v85, v16, v17, vcc
	s_waitcnt lgkmcnt(9)
	v_sub_f32_e32 v17, v23, v231
	v_add_f32_e32 v17, v102, v17
	v_cmp_gt_u32_e32 vcc, 16, v15
	v_or_b32_e32 v15, 43, v14
	v_sub_u32_e32 v15, v15, v232
	v_cndmask_b32_e32 v86, v16, v17, vcc
	s_waitcnt lgkmcnt(8)
	v_sub_f32_e32 v17, v24, v231
	v_add_f32_e32 v17, v103, v17
	v_cmp_gt_u32_e32 vcc, 16, v15
	v_or_b32_e32 v15, 48, v14
	v_sub_u32_e32 v15, v15, v232
	v_cndmask_b32_e32 v87, v16, v17, vcc
	s_waitcnt lgkmcnt(7)
	v_sub_f32_e32 v17, v25, v231
	v_add_f32_e32 v17, v104, v17
	v_cmp_gt_u32_e32 vcc, 16, v15
	v_or_b32_e32 v15, 49, v14
	v_sub_u32_e32 v15, v15, v232
	v_cndmask_b32_e32 v88, v16, v17, vcc
	s_waitcnt lgkmcnt(6)
	v_sub_f32_e32 v17, v26, v231
	v_add_f32_e32 v17, v105, v17
	v_cmp_gt_u32_e32 vcc, 16, v15
	v_or_b32_e32 v15, 50, v14
	v_sub_u32_e32 v15, v15, v232
	v_cndmask_b32_e32 v89, v16, v17, vcc
	s_waitcnt lgkmcnt(5)
	v_sub_f32_e32 v17, v27, v231
	v_add_f32_e32 v17, v106, v17
	v_cmp_gt_u32_e32 vcc, 16, v15
	v_or_b32_e32 v15, 51, v14
	v_sub_u32_e32 v15, v15, v232
	v_cndmask_b32_e32 v90, v16, v17, vcc
	s_waitcnt lgkmcnt(4)
	v_sub_f32_e32 v17, v28, v231
	v_add_f32_e32 v17, v107, v17
	v_cmp_gt_u32_e32 vcc, 16, v15
	v_or_b32_e32 v15, 56, v14
	v_sub_u32_e32 v15, v15, v232
	v_cndmask_b32_e32 v91, v16, v17, vcc
	s_waitcnt lgkmcnt(3)
	v_sub_f32_e32 v17, v29, v231
	v_add_f32_e32 v17, v108, v17
	v_cmp_gt_u32_e32 vcc, 16, v15
	v_or_b32_e32 v15, 57, v14
	v_sub_u32_e32 v15, v15, v232
	v_cndmask_b32_e32 v92, v16, v17, vcc
	s_waitcnt lgkmcnt(2)
	v_sub_f32_e32 v17, v30, v231
	v_add_f32_e32 v17, v109, v17
	v_cmp_gt_u32_e32 vcc, 16, v15
	v_or_b32_e32 v15, 58, v14
	v_sub_u32_e32 v15, v15, v232
	v_cndmask_b32_e32 v93, v16, v17, vcc
	s_waitcnt lgkmcnt(1)
	v_sub_f32_e32 v17, v31, v231
	v_or_b32_e32 v14, 59, v14
	v_add_f32_e32 v17, v110, v17
	v_cmp_gt_u32_e32 vcc, 16, v15
	v_sub_u32_e32 v14, v14, v232
	s_waitcnt lgkmcnt(0)
	v_sub_f32_e32 v15, v95, v231
	v_cndmask_b32_e32 v94, v16, v17, vcc
	v_add_f32_e32 v15, v111, v15
	v_cmp_gt_u32_e32 vcc, 16, v14
	s_nop 1
	v_cndmask_b32_e32 v95, v16, v15, vcc
	s_branch .LBB0_857
